# NA iteration loop: back edge rotated in front of the loop-back barrier (asm guide 7.11); barrier is the loop head, exit path has its own copy
# baseline (speedup 1.0000x reference)
.Lna_tb_done1:
	s_lshl_b32 s1, s1, 15
	s_lshl_b32 s2, s43, 8
	s_add_u32 s1, s1, s2
	s_add_u32 s1, s1, 0x2000
	s_add_u32 s54, s26, s1
	s_addc_u32 s55, s27, 0
	s_add_u32 s56, s54, 0x2000
	s_addc_u32 s57, s55, 0
	global_load_dwordx4 v[96:99], v194, s[54:55]
	global_load_dwordx4 v[100:103], v194, s[56:57]
	global_load_dwordx4 v[104:107], v195, s[54:55]
	global_load_dwordx4 v[108:111], v195, s[56:57]
	s_waitcnt lgkmcnt(0)
	s_branch .Lna_itloop

.Lna_tb_done2:
	s_lshl_b32 s1, s1, 15
	s_lshl_b32 s2, s43, 8
	s_add_u32 s1, s1, s2
	s_add_u32 s1, s1, 0x2000
	s_add_u32 s54, s26, s1
	s_addc_u32 s55, s27, 0
	s_add_u32 s56, s54, 0x2000
	s_addc_u32 s57, s55, 0
	global_load_dwordx4 v[96:99], v194, s[54:55]
	global_load_dwordx4 v[100:103], v194, s[56:57]
	global_load_dwordx4 v[104:107], v195, s[54:55]
	global_load_dwordx4 v[108:111], v195, s[56:57]
	s_waitcnt lgkmcnt(0)
.Lna_itloop:
	s_mov_b32 s52, 0
	s_mov_b32 s66, 0
.Lna_it_bar:
	s_barrier

.Lna_nostore:
	s_waitcnt lgkmcnt(0)
	s_sub_u32 s66, 0x9000, s66
	s_add_u32 s52, s52, 1
	s_cmp_lt_u32 s52, s51
	s_cbranch_scc1 .Lna_it_bar
	s_barrier
	global_load_dwordx4 v[128:131], v211, s[16:17] offset:0
	global_load_dwordx4 v[132:135], v211, s[16:17] offset:64
	global_load_dwordx4 v[136:139], v211, s[16:17] offset:128
	global_load_dwordx4 v[140:143], v211, s[16:17] offset:192
	s_add_u32 s15, s40, s94
	s_cmp_lt_u32 s15, s41
	s_cselect_b32 s40, s15, s40
	s_cmp_ge_u32 s40, 0x400
	s_cbranch_scc1 .Lna_dec_ctx_1
	s_mov_b32 s45, 0
	s_cmp_eq_u32 s94, 0x100
	s_cbranch_scc0 .Lna_dec_gen_1
	s_lshr_b32 s1, s40, 8
	s_and_b32 s2, s40, 0xff
	s_lshl_b32 s1, s1, 5
	s_and_b32 s4, s2, 7
	s_lshl_b32 s4, s4, 2
	s_add_u32 s1, s1, s4
	s_lshr_b32 s4, s2, 6
	s_add_u32 s1, s1, s4
	s_bfe_u32 s44, s2, 0x30003
	s_lshr_b32 s4, s40, 7
	s_and_b32 s4, s4, 6
	s_add_u32 s44, s44, s4
	s_and_b32 s44, s44, 7
	s_branch .Lna_dec_l2_1
